# phase-6 H stores non-temporal as well (256 MiB streamed out, read back only in phase 7)
# speedup vs baseline: 1.0076x; 1.0076x over previous
;     __device__ __forceinline__ void operator()(const f32x4 (&acc)[2][2][4][2], const pg8::Unit& u, int wr, int wc, int fr, int fq) const {
;         f32x4 sq[2][4];
; #pragma unroll
;         for (int ai = 0; ai < 2; ++ai)
; #pragma unroll
;             for (int m = 0; m < 4; ++m) sq[ai][m] = *(const f32x4*)(ssqp + (size_t)(u.pm * 256 + ai * 128 + wr * 64 + m * 16 + fr) * 4);
;         __builtin_amdgcn_sched_barrier(0);
; #pragma unroll
;         for (int ai = 0; ai < 2; ++ai)
; #pragma unroll
;             for (int m = 0; m < 4; ++m) {
;                 const int row = u.pm * 256 + ai * 128 + wr * 64 + m * 16 + fr;
;                 const float tot = (sq[ai][m].x + sq[ai][m].y) + (sq[ai][m].z + sq[ai][m].w);
;                 const float rn = rsqrtf(tot * (1.f / 1024.f) + EPS);
; #pragma unroll
;                 for (int bj = 0; bj < 2; ++bj) {
;                     float y[8];
; #pragma unroll
;                     for (int n = 0; n < 2; ++n)
; #pragma unroll
;                         for (int e = 0; e < 4; ++e) { const float h = fmaxf(acc[ai][bj][m][n][e] * rn, 0.f); y[n * 4 + e] = h * h; }
;                     store8(H + (size_t)row * FF + u.pn * 256 + 128 * bj + 32 * wc + 8 * fq, y);
;                 }
;             }
.Lh_ok:
	v_lshl_add_u32 v166, s30, 8, v174
	v_or_b32_e32 v198, 16, v166
	v_ashrrev_i32_e32 v167, 31, v166
	v_ashrrev_i32_e32 v199, 31, v198
	v_or_b32_e32 v200, 32, v166
	v_or_b32_e32 v172, 48, v166
	v_lshl_add_u64 v[128:129], v[166:167], 4, s[8:9]
	v_lshl_add_u64 v[130:131], v[198:199], 4, s[8:9]
	v_ashrrev_i32_e32 v201, 31, v200
	v_ashrrev_i32_e32 v173, 31, v172
	v_add_u32_e32 v170, 0x80, v166
	v_add_u32_e32 v168, 0x90, v166
	global_load_dwordx4 v[180:183], v[128:129], off
	global_load_dwordx4 v[186:189], v[130:131], off
	v_lshl_add_u64 v[128:129], v[200:201], 4, s[8:9]
	v_lshl_add_u64 v[130:131], v[172:173], 4, s[8:9]
	v_ashrrev_i32_e32 v171, 31, v170
	v_ashrrev_i32_e32 v169, 31, v168
	v_add_u32_e32 v164, 0xa0, v166
	v_add_u32_e32 v162, 0xb0, v166
	global_load_dwordx4 v[190:193], v[128:129], off
	global_load_dwordx4 v[194:197], v[130:131], off
	v_lshl_add_u64 v[128:129], v[170:171], 4, s[8:9]
	v_lshl_add_u64 v[130:131], v[168:169], 4, s[8:9]
	v_ashrrev_i32_e32 v165, 31, v164
	v_ashrrev_i32_e32 v163, 31, v162
	global_load_dwordx4 v[140:143], v[128:129], off
	global_load_dwordx4 v[136:139], v[130:131], off
	v_lshl_add_u64 v[128:129], v[164:165], 4, s[8:9]
	v_lshl_add_u64 v[130:131], v[162:163], 4, s[8:9]
	global_load_dwordx4 v[132:135], v[128:129], off
	s_nop 0
	global_load_dwordx4 v[128:131], v[130:131], off
	v_lshlrev_b64 v[166:167], 13, v[166:167]
	s_waitcnt vmcnt(0)
	v_mov_b32_e32 v202, v181
	v_mov_b32_e32 v203, v182
	v_mov_b32_e32 v181, v183
	v_lshl_add_u64 v[182:183], s[10:11], 0, v[166:167]
	v_mov_b32_e32 v166, v187
	v_mov_b32_e32 v167, v188
	v_mov_b32_e32 v187, v189
	v_pk_add_f32 v[180:181], v[202:203], v[180:181]
	v_pk_add_f32 v[166:167], v[166:167], v[186:187]
	v_mov_b32_e32 v187, v180
	v_mov_b32_e32 v186, v166
	v_mov_b32_e32 v180, v167
	v_pk_add_f32 v[180:181], v[186:187], v[180:181]
	v_mov_b64_e32 v[166:167], s[20:21]
	v_pk_fma_f32 v[180:181], v[180:181], s[18:19], v[166:167] op_sel_hi:[1,0,0]
	s_lshl_b32 s30, s31, 8
	v_mul_f32_e32 v179, 0x4b800000, v181
	v_cmp_gt_f32_e32 vcc, s50, v181
	s_ashr_i32 s31, s30, 31
	s_lshl_b64 s[30:31], s[30:31], 1
	v_cndmask_b32_e32 v179, v181, v179, vcc
	v_rsq_f32_e32 v179, v179
	v_lshl_add_u64 v[182:183], v[182:183], 0, s[30:31]
	v_lshl_add_u64 v[182:183], v[182:183], 0, s[4:5]
	v_lshl_add_u64 v[182:183], v[182:183], 0, v[152:153]
	v_mul_f32_e32 v181, 0x45800000, v179
	v_cndmask_b32_e32 v179, v179, v181, vcc
	v_mul_f32_e32 v120, v120, v179
	v_max_f32_e32 v120, 0, v120
	v_mul_f32_e32 v181, v120, v120
	v_mul_f32_e32 v120, v121, v179
	v_max_f32_e32 v120, 0, v120
	v_mul_f32_e32 v185, v120, v120
	v_mul_f32_e32 v120, v122, v179
	v_max_f32_e32 v120, 0, v120
	v_mul_f32_e32 v124, v124, v179
	v_mul_f32_e32 v125, v125, v179
	v_mul_f32_e32 v186, v120, v120
	v_mul_f32_e32 v120, v123, v179
	v_max_f32_e32 v124, 0, v124
	v_max_f32_e32 v125, 0, v125
	v_mul_f32_e32 v126, v126, v179
	v_mul_f32_e32 v127, v127, v179
	v_max_f32_e32 v120, 0, v120
	v_mul_f32_e32 v112, v112, v179
	v_mul_f32_e32 v124, v124, v124
	v_mul_f32_e32 v125, v125, v125
	v_max_f32_e32 v126, 0, v126
	v_max_f32_e32 v127, 0, v127
	v_mul_f32_e32 v123, v120, v120
	v_cvt_pk_bf16_f32 v120, v124, v125
	v_max_f32_e32 v112, 0, v112
	v_mul_f32_e32 v126, v126, v126
	v_mul_f32_e32 v127, v127, v127
	v_cvt_pk_bf16_f32 v121, v126, v127
	v_cvt_pk_bf16_f32 v122, v181, v185
	v_cvt_pk_bf16_f32 v123, v186, v123
	global_store_dwordx4 v[182:183], v[120:123], off nt
	v_mul_f32_e32 v116, v116, v179
	v_max_f32_e32 v116, 0, v116
	v_mul_f32_e32 v120, v112, v112
	v_mul_f32_e32 v112, v113, v179
	v_max_f32_e32 v112, 0, v112
	v_mul_f32_e32 v121, v112, v112
	v_mul_f32_e32 v112, v114, v179
	v_max_f32_e32 v112, 0, v112
	v_mul_f32_e32 v117, v117, v179
	v_mul_f32_e32 v122, v112, v112
	v_mul_f32_e32 v112, v115, v179
	v_mul_f32_e32 v114, 0x4b800000, v180
	v_cmp_gt_f32_e32 vcc, s50, v180
	v_mul_f32_e32 v116, v116, v116
	v_max_f32_e32 v117, 0, v117
	v_max_f32_e32 v112, 0, v112
	v_cndmask_b32_e32 v114, v180, v114, vcc
	v_mul_f32_e32 v117, v117, v117
	v_mul_f32_e32 v115, v112, v112
	v_cvt_pk_bf16_f32 v112, v116, v117
	v_rsq_f32_e32 v116, v114
	v_mul_f32_e32 v118, v118, v179
	v_mul_f32_e32 v119, v119, v179
	v_max_f32_e32 v118, 0, v118
	v_max_f32_e32 v119, 0, v119
	v_mul_f32_e32 v118, v118, v118
	v_mul_f32_e32 v119, v119, v119
	v_cvt_pk_bf16_f32 v113, v118, v119
	v_cvt_pk_bf16_f32 v114, v120, v121
	v_cvt_pk_bf16_f32 v115, v122, v115
	global_store_dwordx4 v[182:183], v[112:115], off offset:256 nt
	s_nop 1
	v_mul_f32_e32 v112, 0x45800000, v116
	v_cndmask_b32_e32 v114, v116, v112, vcc
	v_mul_f32_e32 v104, v104, v114
	v_max_f32_e32 v104, 0, v104
	v_mul_f32_e32 v117, v104, v104
	v_mul_f32_e32 v104, v105, v114
	v_mul_f32_e32 v108, v108, v114
	v_max_f32_e32 v104, 0, v104
	v_max_f32_e32 v108, 0, v108
	v_mul_f32_e32 v118, v104, v104
	v_mul_f32_e32 v104, v106, v114
	v_mul_f32_e32 v115, v108, v108
	v_mul_f32_e32 v108, v109, v114
	v_max_f32_e32 v104, 0, v104
	v_max_f32_e32 v108, 0, v108
	v_mul_f32_e32 v119, v104, v104
	v_mul_f32_e32 v104, v107, v114
	v_lshlrev_b64 v[112:113], 13, v[198:199]
	v_mul_f32_e32 v116, v108, v108
	v_mul_f32_e32 v108, v110, v114
	v_max_f32_e32 v104, 0, v104
	v_max_f32_e32 v108, 0, v108
	v_mul_f32_e32 v107, v104, v104
	v_lshl_add_u64 v[104:105], s[10:11], 0, v[112:113]
	v_mul_f32_e32 v110, v108, v108
	v_mul_f32_e32 v108, v111, v114
	v_lshl_add_u64 v[104:105], v[104:105], 0, s[30:31]
	v_max_f32_e32 v108, 0, v108
	v_lshl_add_u64 v[104:105], v[104:105], 0, s[4:5]
	v_mul_f32_e32 v96, v96, v114
	v_mul_f32_e32 v111, v108, v108
	v_lshl_add_u64 v[108:109], v[104:105], 0, v[152:153]
	v_cvt_pk_bf16_f32 v104, v115, v116
	v_max_f32_e32 v96, 0, v96
	v_cvt_pk_bf16_f32 v105, v110, v111
;     __device__ __forceinline__ void operator()(const f32x4 (&acc)[2][2][4][2], const pg8::Unit& u, int wr, int wc, int fr, int fq) const {
;     ...
;         for (int ai = 0; ai < 2; ++ai)
; #pragma unroll
;             for (int m = 0; m < 4; ++m) {
;                 const int row = u.pm * 256 + ai * 128 + wr * 64 + m * 16 + fr;
;                 const float tot = (sq[ai][m].x + sq[ai][m].y) + (sq[ai][m].z + sq[ai][m].w);
;                 const float rn = rsqrtf(tot * (1.f / 1024.f) + EPS);
; #pragma unroll
;                 for (int bj = 0; bj < 2; ++bj) {
;                     float y[8];
; #pragma unroll
;                     for (int n = 0; n < 2; ++n)
; #pragma unroll
;                         for (int e = 0; e < 4; ++e) { const float h = fmaxf(acc[ai][bj][m][n][e] * rn, 0.f); y[n * 4 + e] = h * h; }
;                     store8(H + (size_t)row * FF + u.pn * 256 + 128 * bj + 32 * wc + 8 * fq, y);
;                 }
	v_cvt_pk_bf16_f32 v106, v117, v118
	v_cvt_pk_bf16_f32 v107, v119, v107
	global_store_dwordx4 v[108:109], v[104:107], off nt
	v_mul_f32_e32 v100, v100, v114
	v_mul_f32_e32 v101, v101, v114
	v_mul_f32_e32 v104, v96, v96
	v_mul_f32_e32 v96, v97, v114
	v_max_f32_e32 v96, 0, v96
	v_mul_f32_e32 v105, v96, v96
	v_mul_f32_e32 v96, v98, v114
	v_max_f32_e32 v96, 0, v96
	v_mul_f32_e32 v102, v102, v114
	v_mul_f32_e32 v103, v103, v114
	v_mul_f32_e32 v106, v96, v96
	v_mul_f32_e32 v96, v99, v114
	v_max_f32_e32 v100, 0, v100
	v_max_f32_e32 v101, 0, v101
	v_max_f32_e32 v102, 0, v102
	v_max_f32_e32 v103, 0, v103
	v_max_f32_e32 v96, 0, v96
	v_mul_f32_e32 v100, v100, v100
	v_mul_f32_e32 v101, v101, v101
	v_mul_f32_e32 v102, v102, v102
	v_mul_f32_e32 v103, v103, v103
	v_mul_f32_e32 v99, v96, v96
	v_cvt_pk_bf16_f32 v96, v100, v101
	v_cvt_pk_bf16_f32 v97, v102, v103
	v_cvt_pk_bf16_f32 v98, v104, v105
	v_cvt_pk_bf16_f32 v99, v106, v99
	global_store_dwordx4 v[108:109], v[96:99], off offset:256 nt
	v_mov_b32_e32 v100, v195
	v_mov_b32_e32 v101, v196
	v_mov_b32_e32 v96, v191
	v_mov_b32_e32 v97, v192
	v_mov_b32_e32 v191, v193
	v_mov_b32_e32 v195, v197
	v_pk_add_f32 v[96:97], v[96:97], v[190:191]
	v_pk_add_f32 v[100:101], v[100:101], v[194:195]
	v_mov_b32_e32 v103, v96
	v_mov_b32_e32 v102, v100
	v_mov_b32_e32 v96, v101
	v_pk_add_f32 v[96:97], v[102:103], v[96:97]
	v_lshlrev_b64 v[98:99], 13, v[200:201]
	v_pk_fma_f32 v[96:97], v[96:97], s[18:19], v[166:167] op_sel_hi:[1,0,0]
	v_lshl_add_u64 v[98:99], s[10:11], 0, v[98:99]
	v_mul_f32_e32 v100, 0x4b800000, v97
	v_cmp_gt_f32_e32 vcc, s50, v97
	v_lshl_add_u64 v[98:99], v[98:99], 0, s[30:31]
	v_lshl_add_u64 v[98:99], v[98:99], 0, s[4:5]
	v_cndmask_b32_e32 v97, v97, v100, vcc
	v_rsq_f32_e32 v97, v97
	v_lshl_add_u64 v[98:99], v[98:99], 0, v[152:153]
	v_mul_f32_e32 v100, 0x45800000, v97
	v_cndmask_b32_e32 v97, v97, v100, vcc
	v_mul_f32_e32 v88, v88, v97
	v_max_f32_e32 v88, 0, v88
	v_mul_f32_e32 v100, v88, v88
	v_mul_f32_e32 v88, v89, v97
	v_max_f32_e32 v88, 0, v88
	v_mul_f32_e32 v101, v88, v88
	v_mul_f32_e32 v88, v90, v97
	v_max_f32_e32 v88, 0, v88
	v_mul_f32_e32 v92, v92, v97
	v_mul_f32_e32 v93, v93, v97
	v_mul_f32_e32 v102, v88, v88
	v_mul_f32_e32 v88, v91, v97
	v_max_f32_e32 v92, 0, v92
	v_max_f32_e32 v93, 0, v93
	v_mul_f32_e32 v94, v94, v97
	v_mul_f32_e32 v95, v95, v97
	v_max_f32_e32 v88, 0, v88
	v_mul_f32_e32 v80, v80, v97
	v_mul_f32_e32 v92, v92, v92
	v_mul_f32_e32 v93, v93, v93
	v_max_f32_e32 v94, 0, v94
	v_max_f32_e32 v95, 0, v95
	v_mul_f32_e32 v91, v88, v88
	v_cvt_pk_bf16_f32 v88, v92, v93
	v_max_f32_e32 v80, 0, v80
	v_mul_f32_e32 v94, v94, v94
	v_mul_f32_e32 v95, v95, v95
	v_cvt_pk_bf16_f32 v89, v94, v95
	v_cvt_pk_bf16_f32 v90, v100, v101
	v_cvt_pk_bf16_f32 v91, v102, v91
	global_store_dwordx4 v[98:99], v[88:91], off nt
	v_mul_f32_e32 v84, v84, v97
	v_max_f32_e32 v84, 0, v84
	v_mul_f32_e32 v88, v80, v80
	v_mul_f32_e32 v80, v81, v97
	v_max_f32_e32 v80, 0, v80
	v_mul_f32_e32 v89, v80, v80
	v_mul_f32_e32 v80, v82, v97
	v_max_f32_e32 v80, 0, v80
	v_mul_f32_e32 v85, v85, v97
	v_mul_f32_e32 v90, v80, v80
	v_mul_f32_e32 v80, v83, v97
	v_mul_f32_e32 v82, 0x4b800000, v96
	v_cmp_gt_f32_e32 vcc, s50, v96
	v_mul_f32_e32 v84, v84, v84
	v_max_f32_e32 v85, 0, v85
	v_max_f32_e32 v80, 0, v80
	v_cndmask_b32_e32 v82, v96, v82, vcc
	v_mul_f32_e32 v85, v85, v85
	v_mul_f32_e32 v83, v80, v80
	v_cvt_pk_bf16_f32 v80, v84, v85
	v_rsq_f32_e32 v84, v82
	v_mul_f32_e32 v86, v86, v97
	v_mul_f32_e32 v87, v87, v97
	v_max_f32_e32 v86, 0, v86
	v_max_f32_e32 v87, 0, v87
	v_mul_f32_e32 v86, v86, v86
	v_mul_f32_e32 v87, v87, v87
	v_cvt_pk_bf16_f32 v81, v86, v87
	v_cvt_pk_bf16_f32 v82, v88, v89
	v_cvt_pk_bf16_f32 v83, v90, v83
	global_store_dwordx4 v[98:99], v[80:83], off offset:256 nt
	s_nop 1
	v_mul_f32_e32 v80, 0x45800000, v84
	v_cndmask_b32_e32 v82, v84, v80, vcc
	v_mul_f32_e32 v72, v72, v82
	v_max_f32_e32 v72, 0, v72
	v_mul_f32_e32 v85, v72, v72
	v_mul_f32_e32 v72, v73, v82
	v_mul_f32_e32 v76, v76, v82
	v_max_f32_e32 v72, 0, v72
	v_max_f32_e32 v76, 0, v76
	v_mul_f32_e32 v86, v72, v72
	v_mul_f32_e32 v72, v74, v82
	v_mul_f32_e32 v83, v76, v76
	v_mul_f32_e32 v76, v77, v82
	v_max_f32_e32 v72, 0, v72
	v_max_f32_e32 v76, 0, v76
	v_mul_f32_e32 v87, v72, v72
	v_mul_f32_e32 v72, v75, v82
	v_lshlrev_b64 v[80:81], 13, v[172:173]
	v_mul_f32_e32 v84, v76, v76
	v_mul_f32_e32 v76, v78, v82
	v_max_f32_e32 v72, 0, v72
	v_max_f32_e32 v76, 0, v76
	v_mul_f32_e32 v75, v72, v72
	v_lshl_add_u64 v[72:73], s[10:11], 0, v[80:81]
	v_mul_f32_e32 v78, v76, v76
	v_mul_f32_e32 v76, v79, v82
	v_lshl_add_u64 v[72:73], v[72:73], 0, s[30:31]
	v_max_f32_e32 v76, 0, v76
	v_lshl_add_u64 v[72:73], v[72:73], 0, s[4:5]
	v_mul_f32_e32 v64, v64, v82
	v_mul_f32_e32 v79, v76, v76
	v_lshl_add_u64 v[76:77], v[72:73], 0, v[152:153]
	v_cvt_pk_bf16_f32 v72, v83, v84
	v_max_f32_e32 v64, 0, v64
	v_cvt_pk_bf16_f32 v73, v78, v79
	v_cvt_pk_bf16_f32 v74, v85, v86
	v_cvt_pk_bf16_f32 v75, v87, v75
	global_store_dwordx4 v[76:77], v[72:75], off nt
	v_mul_f32_e32 v68, v68, v82
	v_mul_f32_e32 v69, v69, v82
	v_mul_f32_e32 v72, v64, v64
	v_mul_f32_e32 v64, v65, v82
	v_max_f32_e32 v64, 0, v64
	v_mul_f32_e32 v73, v64, v64
	v_mul_f32_e32 v64, v66, v82
	v_max_f32_e32 v64, 0, v64
	v_mul_f32_e32 v70, v70, v82
	v_mul_f32_e32 v71, v71, v82
	v_mul_f32_e32 v74, v64, v64
	v_mul_f32_e32 v64, v67, v82
	v_max_f32_e32 v68, 0, v68
	v_max_f32_e32 v69, 0, v69
	v_max_f32_e32 v70, 0, v70
	v_max_f32_e32 v71, 0, v71
	v_max_f32_e32 v64, 0, v64
	v_mul_f32_e32 v68, v68, v68
	v_mul_f32_e32 v69, v69, v69
	v_mul_f32_e32 v70, v70, v70
	v_mul_f32_e32 v71, v71, v71
	v_mul_f32_e32 v67, v64, v64
	v_cvt_pk_bf16_f32 v64, v68, v69
;     __device__ __forceinline__ void operator()(const f32x4 (&acc)[2][2][4][2], const pg8::Unit& u, int wr, int wc, int fr, int fq) const {
;     ...
;         for (int ai = 0; ai < 2; ++ai)
; #pragma unroll
;             for (int m = 0; m < 4; ++m) {
;                 const int row = u.pm * 256 + ai * 128 + wr * 64 + m * 16 + fr;
;                 const float tot = (sq[ai][m].x + sq[ai][m].y) + (sq[ai][m].z + sq[ai][m].w);
;                 const float rn = rsqrtf(tot * (1.f / 1024.f) + EPS);
; #pragma unroll
;                 for (int bj = 0; bj < 2; ++bj) {
;                     float y[8];
; #pragma unroll
;                     for (int n = 0; n < 2; ++n)
; #pragma unroll
;                         for (int e = 0; e < 4; ++e) { const float h = fmaxf(acc[ai][bj][m][n][e] * rn, 0.f); y[n * 4 + e] = h * h; }
;                     store8(H + (size_t)row * FF + u.pn * 256 + 128 * bj + 32 * wc + 8 * fq, y);
;                 }
	v_cvt_pk_bf16_f32 v65, v70, v71
	v_cvt_pk_bf16_f32 v66, v72, v73
	v_cvt_pk_bf16_f32 v67, v74, v67
	global_store_dwordx4 v[76:77], v[64:67], off offset:256 nt
	v_mov_b32_e32 v68, v137
	v_mov_b32_e32 v69, v138
	v_mov_b32_e32 v64, v141
	v_mov_b32_e32 v65, v142
	v_mov_b32_e32 v141, v143
	v_mov_b32_e32 v137, v139
	v_pk_add_f32 v[64:65], v[64:65], v[140:141]
	v_pk_add_f32 v[68:69], v[68:69], v[136:137]
	v_mov_b32_e32 v71, v64
	v_mov_b32_e32 v70, v68
	v_mov_b32_e32 v64, v69
	v_pk_add_f32 v[64:65], v[70:71], v[64:65]
	v_lshlrev_b64 v[66:67], 13, v[170:171]
	v_pk_fma_f32 v[64:65], v[64:65], s[18:19], v[166:167] op_sel_hi:[1,0,0]
	v_lshl_add_u64 v[66:67], s[10:11], 0, v[66:67]
	v_mul_f32_e32 v68, 0x4b800000, v65
	v_cmp_gt_f32_e32 vcc, s50, v65
	v_lshl_add_u64 v[66:67], v[66:67], 0, s[30:31]
	v_lshl_add_u64 v[66:67], v[66:67], 0, s[4:5]
	v_cndmask_b32_e32 v65, v65, v68, vcc
	v_rsq_f32_e32 v65, v65
	v_lshl_add_u64 v[66:67], v[66:67], 0, v[152:153]
	v_mul_f32_e32 v68, 0x45800000, v65
	v_cndmask_b32_e32 v65, v65, v68, vcc
	v_mul_f32_e32 v56, v56, v65
	v_max_f32_e32 v56, 0, v56
	v_mul_f32_e32 v68, v56, v56
	v_mul_f32_e32 v56, v57, v65
	v_max_f32_e32 v56, 0, v56
	v_mul_f32_e32 v69, v56, v56
	v_mul_f32_e32 v56, v58, v65
	v_max_f32_e32 v56, 0, v56
	v_mul_f32_e32 v60, v60, v65
	v_mul_f32_e32 v61, v61, v65
	v_mul_f32_e32 v70, v56, v56
	v_mul_f32_e32 v56, v59, v65
	v_max_f32_e32 v60, 0, v60
	v_max_f32_e32 v61, 0, v61
	v_mul_f32_e32 v62, v62, v65
	v_mul_f32_e32 v63, v63, v65
	v_max_f32_e32 v56, 0, v56
	v_mul_f32_e32 v48, v48, v65
	v_mul_f32_e32 v60, v60, v60
	v_mul_f32_e32 v61, v61, v61
	v_max_f32_e32 v62, 0, v62
	v_max_f32_e32 v63, 0, v63
	v_mul_f32_e32 v59, v56, v56
	v_cvt_pk_bf16_f32 v56, v60, v61
	v_max_f32_e32 v48, 0, v48
	v_mul_f32_e32 v62, v62, v62
	v_mul_f32_e32 v63, v63, v63
	v_cvt_pk_bf16_f32 v57, v62, v63
	v_cvt_pk_bf16_f32 v58, v68, v69
	v_cvt_pk_bf16_f32 v59, v70, v59
	global_store_dwordx4 v[66:67], v[56:59], off nt
	v_mul_f32_e32 v52, v52, v65
	v_max_f32_e32 v52, 0, v52
	v_mul_f32_e32 v56, v48, v48
	v_mul_f32_e32 v48, v49, v65
	v_max_f32_e32 v48, 0, v48
	v_mul_f32_e32 v57, v48, v48
	v_mul_f32_e32 v48, v50, v65
	v_max_f32_e32 v48, 0, v48
	v_mul_f32_e32 v53, v53, v65
	v_mul_f32_e32 v58, v48, v48
	v_mul_f32_e32 v48, v51, v65
	v_mul_f32_e32 v50, 0x4b800000, v64
	v_cmp_gt_f32_e32 vcc, s50, v64
	v_mul_f32_e32 v52, v52, v52
	v_max_f32_e32 v53, 0, v53
	v_max_f32_e32 v48, 0, v48
	v_cndmask_b32_e32 v50, v64, v50, vcc
	v_mul_f32_e32 v53, v53, v53
	v_mul_f32_e32 v51, v48, v48
	v_cvt_pk_bf16_f32 v48, v52, v53
	v_rsq_f32_e32 v52, v50
	v_mul_f32_e32 v54, v54, v65
	v_mul_f32_e32 v55, v55, v65
	v_max_f32_e32 v54, 0, v54
	v_max_f32_e32 v55, 0, v55
	v_mul_f32_e32 v54, v54, v54
	v_mul_f32_e32 v55, v55, v55
	v_cvt_pk_bf16_f32 v49, v54, v55
	v_cvt_pk_bf16_f32 v50, v56, v57
	v_cvt_pk_bf16_f32 v51, v58, v51
	global_store_dwordx4 v[66:67], v[48:51], off offset:256 nt
	s_nop 1
	v_mul_f32_e32 v48, 0x45800000, v52
	v_cndmask_b32_e32 v50, v52, v48, vcc
	v_mul_f32_e32 v40, v40, v50
	v_max_f32_e32 v40, 0, v40
	v_mul_f32_e32 v53, v40, v40
	v_mul_f32_e32 v40, v41, v50
	v_mul_f32_e32 v44, v44, v50
	v_max_f32_e32 v40, 0, v40
	v_max_f32_e32 v44, 0, v44
	v_mul_f32_e32 v54, v40, v40
	v_mul_f32_e32 v40, v42, v50
	v_mul_f32_e32 v51, v44, v44
	v_mul_f32_e32 v44, v45, v50
	v_max_f32_e32 v40, 0, v40
	v_max_f32_e32 v44, 0, v44
	v_mul_f32_e32 v55, v40, v40
	v_mul_f32_e32 v40, v43, v50
	v_lshlrev_b64 v[48:49], 13, v[168:169]
	v_mul_f32_e32 v52, v44, v44
	v_mul_f32_e32 v44, v46, v50
	v_max_f32_e32 v40, 0, v40
	v_max_f32_e32 v44, 0, v44
	v_mul_f32_e32 v43, v40, v40
	v_lshl_add_u64 v[40:41], s[10:11], 0, v[48:49]
	v_mul_f32_e32 v46, v44, v44
	v_mul_f32_e32 v44, v47, v50
	v_lshl_add_u64 v[40:41], v[40:41], 0, s[30:31]
	v_max_f32_e32 v44, 0, v44
	v_lshl_add_u64 v[40:41], v[40:41], 0, s[4:5]
	v_mul_f32_e32 v32, v32, v50
	v_mul_f32_e32 v47, v44, v44
	v_lshl_add_u64 v[44:45], v[40:41], 0, v[152:153]
	v_cvt_pk_bf16_f32 v40, v51, v52
	v_max_f32_e32 v32, 0, v32
	v_cvt_pk_bf16_f32 v41, v46, v47
	v_cvt_pk_bf16_f32 v42, v53, v54
	v_cvt_pk_bf16_f32 v43, v55, v43
	global_store_dwordx4 v[44:45], v[40:43], off nt
	v_mul_f32_e32 v36, v36, v50
	v_mul_f32_e32 v37, v37, v50
	v_mul_f32_e32 v40, v32, v32
	v_mul_f32_e32 v32, v33, v50
	v_max_f32_e32 v32, 0, v32
	v_mul_f32_e32 v41, v32, v32
	v_mul_f32_e32 v32, v34, v50
	v_max_f32_e32 v32, 0, v32
	v_mul_f32_e32 v38, v38, v50
	v_mul_f32_e32 v39, v39, v50
	v_mul_f32_e32 v42, v32, v32
	v_mul_f32_e32 v32, v35, v50
	v_max_f32_e32 v36, 0, v36
	v_max_f32_e32 v37, 0, v37
	v_max_f32_e32 v38, 0, v38
	v_max_f32_e32 v39, 0, v39
	v_max_f32_e32 v32, 0, v32
	v_mul_f32_e32 v36, v36, v36
	v_mul_f32_e32 v37, v37, v37
	v_mul_f32_e32 v38, v38, v38
	v_mul_f32_e32 v39, v39, v39
	v_mul_f32_e32 v35, v32, v32
	v_cvt_pk_bf16_f32 v32, v36, v37
	v_cvt_pk_bf16_f32 v33, v38, v39
	v_cvt_pk_bf16_f32 v34, v40, v41
	v_cvt_pk_bf16_f32 v35, v42, v35
;     __device__ __forceinline__ void operator()(const f32x4 (&acc)[2][2][4][2], const pg8::Unit& u, int wr, int wc, int fr, int fq) const {
;     ...
;         for (int ai = 0; ai < 2; ++ai)
; #pragma unroll
;             for (int m = 0; m < 4; ++m) {
;                 const int row = u.pm * 256 + ai * 128 + wr * 64 + m * 16 + fr;
;                 const float tot = (sq[ai][m].x + sq[ai][m].y) + (sq[ai][m].z + sq[ai][m].w);
;                 const float rn = rsqrtf(tot * (1.f / 1024.f) + EPS);
; #pragma unroll
;                 for (int bj = 0; bj < 2; ++bj) {
;                     float y[8];
; #pragma unroll
;                     for (int n = 0; n < 2; ++n)
; #pragma unroll
;                         for (int e = 0; e < 4; ++e) { const float h = fmaxf(acc[ai][bj][m][n][e] * rn, 0.f); y[n * 4 + e] = h * h; }
;                     store8(H + (size_t)row * FF + u.pn * 256 + 128 * bj + 32 * wc + 8 * fq, y);
;                 }
	global_store_dwordx4 v[44:45], v[32:35], off offset:256 nt
	v_mov_b32_e32 v36, v129
	v_mov_b32_e32 v37, v130
	v_mov_b32_e32 v32, v133
	v_mov_b32_e32 v33, v134
	v_mov_b32_e32 v133, v135
	v_mov_b32_e32 v129, v131
	v_pk_add_f32 v[32:33], v[32:33], v[132:133]
	v_pk_add_f32 v[36:37], v[36:37], v[128:129]
	v_mov_b32_e32 v39, v32
	v_mov_b32_e32 v38, v36
	v_mov_b32_e32 v32, v37
	v_pk_add_f32 v[32:33], v[38:39], v[32:33]
	v_lshlrev_b64 v[34:35], 13, v[164:165]
	v_pk_fma_f32 v[32:33], v[32:33], s[18:19], v[166:167] op_sel_hi:[1,0,0]
	v_lshl_add_u64 v[34:35], s[10:11], 0, v[34:35]
	v_mul_f32_e32 v36, 0x4b800000, v33
	v_cmp_gt_f32_e32 vcc, s50, v33
	v_lshl_add_u64 v[34:35], v[34:35], 0, s[30:31]
	v_lshl_add_u64 v[34:35], v[34:35], 0, s[4:5]
	v_cndmask_b32_e32 v33, v33, v36, vcc
	v_rsq_f32_e32 v33, v33
	v_lshl_add_u64 v[34:35], v[34:35], 0, v[152:153]
	v_mul_f32_e32 v36, 0x45800000, v33
	v_cndmask_b32_e32 v33, v33, v36, vcc
	v_mul_f32_e32 v24, v24, v33
	v_max_f32_e32 v24, 0, v24
	v_mul_f32_e32 v36, v24, v24
	v_mul_f32_e32 v24, v25, v33
	v_max_f32_e32 v24, 0, v24
	v_mul_f32_e32 v37, v24, v24
	v_mul_f32_e32 v24, v26, v33
	v_max_f32_e32 v24, 0, v24
	v_mul_f32_e32 v28, v28, v33
	v_mul_f32_e32 v29, v29, v33
	v_mul_f32_e32 v38, v24, v24
	v_mul_f32_e32 v24, v27, v33
	v_max_f32_e32 v28, 0, v28
	v_max_f32_e32 v29, 0, v29
	v_mul_f32_e32 v30, v30, v33
	v_mul_f32_e32 v31, v31, v33
	v_max_f32_e32 v24, 0, v24
	v_mul_f32_e32 v16, v16, v33
	v_mul_f32_e32 v28, v28, v28
	v_mul_f32_e32 v29, v29, v29
	v_max_f32_e32 v30, 0, v30
	v_max_f32_e32 v31, 0, v31
	v_mul_f32_e32 v27, v24, v24
	v_cvt_pk_bf16_f32 v24, v28, v29
	v_max_f32_e32 v16, 0, v16
	v_mul_f32_e32 v30, v30, v30
	v_mul_f32_e32 v31, v31, v31
	v_cvt_pk_bf16_f32 v25, v30, v31
	v_cvt_pk_bf16_f32 v26, v36, v37
	v_cvt_pk_bf16_f32 v27, v38, v27
	global_store_dwordx4 v[34:35], v[24:27], off nt
	v_mul_f32_e32 v20, v20, v33
	v_max_f32_e32 v20, 0, v20
	v_mul_f32_e32 v24, v16, v16
	v_mul_f32_e32 v16, v17, v33
	v_max_f32_e32 v16, 0, v16
	v_mul_f32_e32 v25, v16, v16
	v_mul_f32_e32 v16, v18, v33
	v_max_f32_e32 v16, 0, v16
	v_mul_f32_e32 v21, v21, v33
	v_mul_f32_e32 v26, v16, v16
	v_mul_f32_e32 v16, v19, v33
	v_mul_f32_e32 v18, 0x4b800000, v32
	v_cmp_gt_f32_e32 vcc, s50, v32
	v_mul_f32_e32 v20, v20, v20
	v_max_f32_e32 v21, 0, v21
	v_max_f32_e32 v16, 0, v16
	v_cndmask_b32_e32 v18, v32, v18, vcc
	v_mul_f32_e32 v21, v21, v21
	v_mul_f32_e32 v19, v16, v16
	v_cvt_pk_bf16_f32 v16, v20, v21
	v_rsq_f32_e32 v20, v18
	v_mul_f32_e32 v22, v22, v33
	v_mul_f32_e32 v23, v23, v33
	v_max_f32_e32 v22, 0, v22
	v_max_f32_e32 v23, 0, v23
	v_mul_f32_e32 v22, v22, v22
	v_mul_f32_e32 v23, v23, v23
	v_cvt_pk_bf16_f32 v17, v22, v23
	v_cvt_pk_bf16_f32 v18, v24, v25
	v_cvt_pk_bf16_f32 v19, v26, v19
	global_store_dwordx4 v[34:35], v[16:19], off offset:256 nt
	s_nop 1
	v_mul_f32_e32 v16, 0x45800000, v20
	v_cndmask_b32_e32 v18, v20, v16, vcc
	v_mul_f32_e32 v8, v8, v18
	v_max_f32_e32 v8, 0, v8
	v_mul_f32_e32 v21, v8, v8
	v_mul_f32_e32 v8, v9, v18
	v_mul_f32_e32 v12, v12, v18
	v_max_f32_e32 v8, 0, v8
	v_max_f32_e32 v12, 0, v12
	v_mul_f32_e32 v22, v8, v8
	v_mul_f32_e32 v8, v10, v18
	v_mul_f32_e32 v19, v12, v12
	v_mul_f32_e32 v12, v13, v18
	v_max_f32_e32 v8, 0, v8
	v_max_f32_e32 v12, 0, v12
	v_mul_f32_e32 v23, v8, v8
	v_mul_f32_e32 v8, v11, v18
	v_lshlrev_b64 v[16:17], 13, v[162:163]
	v_mul_f32_e32 v20, v12, v12
	v_mul_f32_e32 v12, v14, v18
	v_max_f32_e32 v8, 0, v8
	v_max_f32_e32 v12, 0, v12
	v_mul_f32_e32 v11, v8, v8
	v_lshl_add_u64 v[8:9], s[10:11], 0, v[16:17]
	v_mul_f32_e32 v14, v12, v12
	v_mul_f32_e32 v12, v15, v18
	v_lshl_add_u64 v[8:9], v[8:9], 0, s[30:31]
	v_max_f32_e32 v12, 0, v12
	v_lshl_add_u64 v[8:9], v[8:9], 0, s[4:5]
	v_mul_f32_e32 v0, v0, v18
	v_mul_f32_e32 v15, v12, v12
	v_lshl_add_u64 v[12:13], v[8:9], 0, v[152:153]
	v_cvt_pk_bf16_f32 v8, v19, v20
	v_max_f32_e32 v0, 0, v0
	v_cvt_pk_bf16_f32 v9, v14, v15
	v_cvt_pk_bf16_f32 v10, v21, v22
	v_cvt_pk_bf16_f32 v11, v23, v11
	global_store_dwordx4 v[12:13], v[8:11], off nt
	v_mul_f32_e32 v4, v4, v18
	v_mul_f32_e32 v5, v5, v18
	v_mul_f32_e32 v8, v0, v0
	v_mul_f32_e32 v0, v1, v18
	v_max_f32_e32 v0, 0, v0
	v_mul_f32_e32 v9, v0, v0
	v_mul_f32_e32 v0, v2, v18
	v_max_f32_e32 v0, 0, v0
	v_mul_f32_e32 v10, v0, v0
	v_mul_f32_e32 v0, v3, v18
	v_mul_f32_e32 v6, v6, v18
	v_mul_f32_e32 v7, v7, v18
	v_max_f32_e32 v0, 0, v0
	v_max_f32_e32 v4, 0, v4
	v_max_f32_e32 v5, 0, v5
	v_max_f32_e32 v6, 0, v6
	v_max_f32_e32 v7, 0, v7
	v_mul_f32_e32 v3, v0, v0
	s_andn2_b64 vcc, exec, s[2:3]
	s_mov_b64 s[2:3], -1
	v_mul_f32_e32 v4, v4, v4
	v_mul_f32_e32 v5, v5, v5
	v_mul_f32_e32 v6, v6, v6
	v_mul_f32_e32 v7, v7, v7
	v_cvt_pk_bf16_f32 v0, v4, v5
	v_cvt_pk_bf16_f32 v1, v6, v7
	v_cvt_pk_bf16_f32 v2, v8, v9
	v_cvt_pk_bf16_f32 v3, v10, v3
	global_store_dwordx4 v[12:13], v[0:3], off offset:256 nt
	s_cbranch_vccnz .LBB0_999
	s_andn2_b64 vcc, exec, s[6:7]
	s_cbranch_vccnz .LBB0_998
	s_barrier
	s_branch .LBB0_998
